# P9 unit order: every CU runs its split-K slice unit first and the full prompt tile second (slab stores overlap the long tile mainloop)
# speedup vs baseline: 1.0045x; 1.0045x over previous
.LBB0_1580:
	v_readlane_b32 s0, v245, 35
	s_cmp_lt_i32 s0, 10
	v_readlane_b32 s1, v245, 36
	s_cselect_b64 s[8:9], -1, 0
	s_and_b64 s[0:1], s[8:9], s[6:7]
	s_andn2_b64 vcc, exec, s[0:1]
	s_cbranch_vccnz .LBB0_1620
	s_mov_b32 s77, 1
	s_lshl_b32 s78, s77, 8
	s_add_i32 s78, s78, s96
	s_cmpk_gt_i32 s78, 0x1ff
	v_readfirstlane_b32 s20, v0
	s_cbranch_scc1 .LBB0_1620
	s_add_i32 s0, s78, 0xffffff00
	s_cmpk_lt_i32 s78, 0x100
	s_cselect_b64 s[6:7], -1, 0
	s_and_b64 vcc, s[6:7], exec
	s_cselect_b32 s0, s78, s0
	s_ashr_i32 s14, s0, 5
	s_mov_b32 s12, 0
	s_mov_b32 s10, -1
	s_cbranch_vccnz .LBB0_1588
	s_cmp_gt_i32 s14, 5
	s_cbranch_scc0 .LBB0_1585
	s_lshl_b32 s1, s14, 2
	s_add_i32 s12, s1, 12
	s_cbranch_execz .LBB0_1586
	s_branch .LBB0_1587
